# prep cvec items: 128-iteration serialized load-wait-fmac loop pipelined as 8 batches of 16 (same FMA order) - was the prep critical path before the first grid sync
# baseline (speedup 1.0000x reference)
; DI void prep_phase(int ws, PP p, char* shm) {
;     ...
;       const int q = it - n_tr - n_mod, kv = q >> 2, n = (q & 3) * 32 + (tid & 31), kg = tid >> 5;
;       const float* w1 = p->cmp_w1 + (long)kv * 2048 * 128;
;       const float* pe = p->cmp_pos + (long)kv * 2048;
;       float a = 0.f;
;       for (int k = kg * 128; k < kg * 128 + 128; ++k) a += pe[k] * w1[(long)k * 128 + n];
.LBB0_27:
	global_load_dword v160, v[4:5], off
	global_load_dword v161, v[2:3], off
	v_lshl_add_u64 v[2:3], v[2:3], 0, s[34:35]
	v_lshl_add_u64 v[4:5], v[4:5], 0, 4
	global_load_dword v162, v[4:5], off
	global_load_dword v163, v[2:3], off
	v_lshl_add_u64 v[2:3], v[2:3], 0, s[34:35]
	v_lshl_add_u64 v[4:5], v[4:5], 0, 4
	global_load_dword v164, v[4:5], off
	global_load_dword v165, v[2:3], off
	v_lshl_add_u64 v[2:3], v[2:3], 0, s[34:35]
	v_lshl_add_u64 v[4:5], v[4:5], 0, 4
	global_load_dword v166, v[4:5], off
	global_load_dword v167, v[2:3], off
	v_lshl_add_u64 v[2:3], v[2:3], 0, s[34:35]
	v_lshl_add_u64 v[4:5], v[4:5], 0, 4
	global_load_dword v168, v[4:5], off
	global_load_dword v169, v[2:3], off
	v_lshl_add_u64 v[2:3], v[2:3], 0, s[34:35]
	v_lshl_add_u64 v[4:5], v[4:5], 0, 4
	global_load_dword v170, v[4:5], off
	global_load_dword v171, v[2:3], off
	v_lshl_add_u64 v[2:3], v[2:3], 0, s[34:35]
	v_lshl_add_u64 v[4:5], v[4:5], 0, 4
	global_load_dword v172, v[4:5], off
	global_load_dword v173, v[2:3], off
	v_lshl_add_u64 v[2:3], v[2:3], 0, s[34:35]
	v_lshl_add_u64 v[4:5], v[4:5], 0, 4
	global_load_dword v174, v[4:5], off
	global_load_dword v175, v[2:3], off
	v_lshl_add_u64 v[2:3], v[2:3], 0, s[34:35]
	v_lshl_add_u64 v[4:5], v[4:5], 0, 4
	global_load_dword v176, v[4:5], off
	global_load_dword v177, v[2:3], off
	v_lshl_add_u64 v[2:3], v[2:3], 0, s[34:35]
	v_lshl_add_u64 v[4:5], v[4:5], 0, 4
	global_load_dword v178, v[4:5], off
	global_load_dword v179, v[2:3], off
	v_lshl_add_u64 v[2:3], v[2:3], 0, s[34:35]
	v_lshl_add_u64 v[4:5], v[4:5], 0, 4
	global_load_dword v180, v[4:5], off
	global_load_dword v181, v[2:3], off
	v_lshl_add_u64 v[2:3], v[2:3], 0, s[34:35]
	v_lshl_add_u64 v[4:5], v[4:5], 0, 4
	global_load_dword v182, v[4:5], off
	global_load_dword v183, v[2:3], off
	v_lshl_add_u64 v[2:3], v[2:3], 0, s[34:35]
	v_lshl_add_u64 v[4:5], v[4:5], 0, 4
	global_load_dword v184, v[4:5], off
	global_load_dword v185, v[2:3], off
	v_lshl_add_u64 v[2:3], v[2:3], 0, s[34:35]
	v_lshl_add_u64 v[4:5], v[4:5], 0, 4
	global_load_dword v186, v[4:5], off
	global_load_dword v187, v[2:3], off
	v_lshl_add_u64 v[2:3], v[2:3], 0, s[34:35]
	v_lshl_add_u64 v[4:5], v[4:5], 0, 4
	global_load_dword v188, v[4:5], off
	global_load_dword v189, v[2:3], off
	v_lshl_add_u64 v[2:3], v[2:3], 0, s[34:35]
	v_lshl_add_u64 v[4:5], v[4:5], 0, 4
	global_load_dword v190, v[4:5], off
	global_load_dword v191, v[2:3], off
	v_lshl_add_u64 v[2:3], v[2:3], 0, s[34:35]
	v_lshl_add_u64 v[4:5], v[4:5], 0, 4
	s_waitcnt vmcnt(30)
	v_fmac_f32_e32 v6, v160, v161
	s_waitcnt vmcnt(28)
	v_fmac_f32_e32 v6, v162, v163
	s_waitcnt vmcnt(26)
	v_fmac_f32_e32 v6, v164, v165
	s_waitcnt vmcnt(24)
	v_fmac_f32_e32 v6, v166, v167
	s_waitcnt vmcnt(22)
	v_fmac_f32_e32 v6, v168, v169
	s_waitcnt vmcnt(20)
	v_fmac_f32_e32 v6, v170, v171
	s_waitcnt vmcnt(18)
	v_fmac_f32_e32 v6, v172, v173
	s_waitcnt vmcnt(16)
	v_fmac_f32_e32 v6, v174, v175
	s_waitcnt vmcnt(14)
	v_fmac_f32_e32 v6, v176, v177
	s_waitcnt vmcnt(12)
	v_fmac_f32_e32 v6, v178, v179
	s_waitcnt vmcnt(10)
	v_fmac_f32_e32 v6, v180, v181
	s_waitcnt vmcnt(8)
	v_fmac_f32_e32 v6, v182, v183
	s_waitcnt vmcnt(6)
	v_fmac_f32_e32 v6, v184, v185
	s_waitcnt vmcnt(4)
	v_fmac_f32_e32 v6, v186, v187
	s_waitcnt vmcnt(2)
	v_fmac_f32_e32 v6, v188, v189
	s_waitcnt vmcnt(0)
	v_fmac_f32_e32 v6, v190, v191
	global_load_dword v160, v[4:5], off
	global_load_dword v161, v[2:3], off
	v_lshl_add_u64 v[2:3], v[2:3], 0, s[34:35]
	v_lshl_add_u64 v[4:5], v[4:5], 0, 4
	global_load_dword v162, v[4:5], off
	global_load_dword v163, v[2:3], off
	v_lshl_add_u64 v[2:3], v[2:3], 0, s[34:35]
	v_lshl_add_u64 v[4:5], v[4:5], 0, 4
	global_load_dword v164, v[4:5], off
	global_load_dword v165, v[2:3], off
	v_lshl_add_u64 v[2:3], v[2:3], 0, s[34:35]
	v_lshl_add_u64 v[4:5], v[4:5], 0, 4
	global_load_dword v166, v[4:5], off
	global_load_dword v167, v[2:3], off
	v_lshl_add_u64 v[2:3], v[2:3], 0, s[34:35]
	v_lshl_add_u64 v[4:5], v[4:5], 0, 4
	global_load_dword v168, v[4:5], off
	global_load_dword v169, v[2:3], off
	v_lshl_add_u64 v[2:3], v[2:3], 0, s[34:35]
	v_lshl_add_u64 v[4:5], v[4:5], 0, 4
	global_load_dword v170, v[4:5], off
	global_load_dword v171, v[2:3], off
	v_lshl_add_u64 v[2:3], v[2:3], 0, s[34:35]
	v_lshl_add_u64 v[4:5], v[4:5], 0, 4
	global_load_dword v172, v[4:5], off
	global_load_dword v173, v[2:3], off
	v_lshl_add_u64 v[2:3], v[2:3], 0, s[34:35]
	v_lshl_add_u64 v[4:5], v[4:5], 0, 4
	global_load_dword v174, v[4:5], off
	global_load_dword v175, v[2:3], off
	v_lshl_add_u64 v[2:3], v[2:3], 0, s[34:35]
	v_lshl_add_u64 v[4:5], v[4:5], 0, 4
	global_load_dword v176, v[4:5], off
	global_load_dword v177, v[2:3], off
	v_lshl_add_u64 v[2:3], v[2:3], 0, s[34:35]
	v_lshl_add_u64 v[4:5], v[4:5], 0, 4
	global_load_dword v178, v[4:5], off
	global_load_dword v179, v[2:3], off
	v_lshl_add_u64 v[2:3], v[2:3], 0, s[34:35]
	v_lshl_add_u64 v[4:5], v[4:5], 0, 4
	global_load_dword v180, v[4:5], off
	global_load_dword v181, v[2:3], off
	v_lshl_add_u64 v[2:3], v[2:3], 0, s[34:35]
	v_lshl_add_u64 v[4:5], v[4:5], 0, 4
	global_load_dword v182, v[4:5], off
	global_load_dword v183, v[2:3], off
	v_lshl_add_u64 v[2:3], v[2:3], 0, s[34:35]
	v_lshl_add_u64 v[4:5], v[4:5], 0, 4
	global_load_dword v184, v[4:5], off
	global_load_dword v185, v[2:3], off
	v_lshl_add_u64 v[2:3], v[2:3], 0, s[34:35]
	v_lshl_add_u64 v[4:5], v[4:5], 0, 4
	global_load_dword v186, v[4:5], off
	global_load_dword v187, v[2:3], off
	v_lshl_add_u64 v[2:3], v[2:3], 0, s[34:35]
	v_lshl_add_u64 v[4:5], v[4:5], 0, 4
	global_load_dword v188, v[4:5], off
	global_load_dword v189, v[2:3], off
	v_lshl_add_u64 v[2:3], v[2:3], 0, s[34:35]
	v_lshl_add_u64 v[4:5], v[4:5], 0, 4
	global_load_dword v190, v[4:5], off
	global_load_dword v191, v[2:3], off
	v_lshl_add_u64 v[2:3], v[2:3], 0, s[34:35]
	v_lshl_add_u64 v[4:5], v[4:5], 0, 4
	s_waitcnt vmcnt(30)
; DI void prep_phase(int ws, PP p, char* shm) {
;     ...
;       const int q = it - n_tr - n_mod, kv = q >> 2, n = (q & 3) * 32 + (tid & 31), kg = tid >> 5;
;       const float* w1 = p->cmp_w1 + (long)kv * 2048 * 128;
;       const float* pe = p->cmp_pos + (long)kv * 2048;
;       float a = 0.f;
;       for (int k = kg * 128; k < kg * 128 + 128; ++k) a += pe[k] * w1[(long)k * 128 + n];
	v_fmac_f32_e32 v6, v160, v161
	s_waitcnt vmcnt(28)
	v_fmac_f32_e32 v6, v162, v163
	s_waitcnt vmcnt(26)
	v_fmac_f32_e32 v6, v164, v165
	s_waitcnt vmcnt(24)
	v_fmac_f32_e32 v6, v166, v167
	s_waitcnt vmcnt(22)
	v_fmac_f32_e32 v6, v168, v169
	s_waitcnt vmcnt(20)
	v_fmac_f32_e32 v6, v170, v171
	s_waitcnt vmcnt(18)
	v_fmac_f32_e32 v6, v172, v173
	s_waitcnt vmcnt(16)
	v_fmac_f32_e32 v6, v174, v175
	s_waitcnt vmcnt(14)
	v_fmac_f32_e32 v6, v176, v177
	s_waitcnt vmcnt(12)
	v_fmac_f32_e32 v6, v178, v179
	s_waitcnt vmcnt(10)
	v_fmac_f32_e32 v6, v180, v181
	s_waitcnt vmcnt(8)
	v_fmac_f32_e32 v6, v182, v183
	s_waitcnt vmcnt(6)
	v_fmac_f32_e32 v6, v184, v185
	s_waitcnt vmcnt(4)
	v_fmac_f32_e32 v6, v186, v187
	s_waitcnt vmcnt(2)
	v_fmac_f32_e32 v6, v188, v189
	s_waitcnt vmcnt(0)
	v_fmac_f32_e32 v6, v190, v191
	global_load_dword v160, v[4:5], off
	global_load_dword v161, v[2:3], off
	v_lshl_add_u64 v[2:3], v[2:3], 0, s[34:35]
	v_lshl_add_u64 v[4:5], v[4:5], 0, 4
	global_load_dword v162, v[4:5], off
	global_load_dword v163, v[2:3], off
	v_lshl_add_u64 v[2:3], v[2:3], 0, s[34:35]
	v_lshl_add_u64 v[4:5], v[4:5], 0, 4
	global_load_dword v164, v[4:5], off
	global_load_dword v165, v[2:3], off
	v_lshl_add_u64 v[2:3], v[2:3], 0, s[34:35]
	v_lshl_add_u64 v[4:5], v[4:5], 0, 4
	global_load_dword v166, v[4:5], off
	global_load_dword v167, v[2:3], off
	v_lshl_add_u64 v[2:3], v[2:3], 0, s[34:35]
	v_lshl_add_u64 v[4:5], v[4:5], 0, 4
	global_load_dword v168, v[4:5], off
	global_load_dword v169, v[2:3], off
	v_lshl_add_u64 v[2:3], v[2:3], 0, s[34:35]
	v_lshl_add_u64 v[4:5], v[4:5], 0, 4
	global_load_dword v170, v[4:5], off
	global_load_dword v171, v[2:3], off
	v_lshl_add_u64 v[2:3], v[2:3], 0, s[34:35]
	v_lshl_add_u64 v[4:5], v[4:5], 0, 4
	global_load_dword v172, v[4:5], off
	global_load_dword v173, v[2:3], off
	v_lshl_add_u64 v[2:3], v[2:3], 0, s[34:35]
	v_lshl_add_u64 v[4:5], v[4:5], 0, 4
	global_load_dword v174, v[4:5], off
	global_load_dword v175, v[2:3], off
	v_lshl_add_u64 v[2:3], v[2:3], 0, s[34:35]
	v_lshl_add_u64 v[4:5], v[4:5], 0, 4
	global_load_dword v176, v[4:5], off
	global_load_dword v177, v[2:3], off
	v_lshl_add_u64 v[2:3], v[2:3], 0, s[34:35]
	v_lshl_add_u64 v[4:5], v[4:5], 0, 4
	global_load_dword v178, v[4:5], off
	global_load_dword v179, v[2:3], off
	v_lshl_add_u64 v[2:3], v[2:3], 0, s[34:35]
	v_lshl_add_u64 v[4:5], v[4:5], 0, 4
	global_load_dword v180, v[4:5], off
	global_load_dword v181, v[2:3], off
	v_lshl_add_u64 v[2:3], v[2:3], 0, s[34:35]
	v_lshl_add_u64 v[4:5], v[4:5], 0, 4
	global_load_dword v182, v[4:5], off
	global_load_dword v183, v[2:3], off
	v_lshl_add_u64 v[2:3], v[2:3], 0, s[34:35]
	v_lshl_add_u64 v[4:5], v[4:5], 0, 4
	global_load_dword v184, v[4:5], off
	global_load_dword v185, v[2:3], off
	v_lshl_add_u64 v[2:3], v[2:3], 0, s[34:35]
	v_lshl_add_u64 v[4:5], v[4:5], 0, 4
	global_load_dword v186, v[4:5], off
	global_load_dword v187, v[2:3], off
	v_lshl_add_u64 v[2:3], v[2:3], 0, s[34:35]
	v_lshl_add_u64 v[4:5], v[4:5], 0, 4
	global_load_dword v188, v[4:5], off
	global_load_dword v189, v[2:3], off
	v_lshl_add_u64 v[2:3], v[2:3], 0, s[34:35]
	v_lshl_add_u64 v[4:5], v[4:5], 0, 4
	global_load_dword v190, v[4:5], off
	global_load_dword v191, v[2:3], off
	v_lshl_add_u64 v[2:3], v[2:3], 0, s[34:35]
	v_lshl_add_u64 v[4:5], v[4:5], 0, 4
	s_waitcnt vmcnt(30)
	v_fmac_f32_e32 v6, v160, v161
	s_waitcnt vmcnt(28)
	v_fmac_f32_e32 v6, v162, v163
	s_waitcnt vmcnt(26)
	v_fmac_f32_e32 v6, v164, v165
	s_waitcnt vmcnt(24)
	v_fmac_f32_e32 v6, v166, v167
	s_waitcnt vmcnt(22)
	v_fmac_f32_e32 v6, v168, v169
	s_waitcnt vmcnt(20)
	v_fmac_f32_e32 v6, v170, v171
	s_waitcnt vmcnt(18)
	v_fmac_f32_e32 v6, v172, v173
	s_waitcnt vmcnt(16)
	v_fmac_f32_e32 v6, v174, v175
	s_waitcnt vmcnt(14)
	v_fmac_f32_e32 v6, v176, v177
	s_waitcnt vmcnt(12)
	v_fmac_f32_e32 v6, v178, v179
	s_waitcnt vmcnt(10)
	v_fmac_f32_e32 v6, v180, v181
	s_waitcnt vmcnt(8)
	v_fmac_f32_e32 v6, v182, v183
	s_waitcnt vmcnt(6)
	v_fmac_f32_e32 v6, v184, v185
	s_waitcnt vmcnt(4)
	v_fmac_f32_e32 v6, v186, v187
	s_waitcnt vmcnt(2)
	v_fmac_f32_e32 v6, v188, v189
	s_waitcnt vmcnt(0)
	v_fmac_f32_e32 v6, v190, v191
	global_load_dword v160, v[4:5], off
	global_load_dword v161, v[2:3], off
	v_lshl_add_u64 v[2:3], v[2:3], 0, s[34:35]
	v_lshl_add_u64 v[4:5], v[4:5], 0, 4
	global_load_dword v162, v[4:5], off
	global_load_dword v163, v[2:3], off
	v_lshl_add_u64 v[2:3], v[2:3], 0, s[34:35]
	v_lshl_add_u64 v[4:5], v[4:5], 0, 4
	global_load_dword v164, v[4:5], off
	global_load_dword v165, v[2:3], off
	v_lshl_add_u64 v[2:3], v[2:3], 0, s[34:35]
	v_lshl_add_u64 v[4:5], v[4:5], 0, 4
	global_load_dword v166, v[4:5], off
	global_load_dword v167, v[2:3], off
	v_lshl_add_u64 v[2:3], v[2:3], 0, s[34:35]
	v_lshl_add_u64 v[4:5], v[4:5], 0, 4
	global_load_dword v168, v[4:5], off
	global_load_dword v169, v[2:3], off
	v_lshl_add_u64 v[2:3], v[2:3], 0, s[34:35]
	v_lshl_add_u64 v[4:5], v[4:5], 0, 4
	global_load_dword v170, v[4:5], off
	global_load_dword v171, v[2:3], off
	v_lshl_add_u64 v[2:3], v[2:3], 0, s[34:35]
	v_lshl_add_u64 v[4:5], v[4:5], 0, 4
	global_load_dword v172, v[4:5], off
	global_load_dword v173, v[2:3], off
	v_lshl_add_u64 v[2:3], v[2:3], 0, s[34:35]
	v_lshl_add_u64 v[4:5], v[4:5], 0, 4
	global_load_dword v174, v[4:5], off
	global_load_dword v175, v[2:3], off
	v_lshl_add_u64 v[2:3], v[2:3], 0, s[34:35]
	v_lshl_add_u64 v[4:5], v[4:5], 0, 4
	global_load_dword v176, v[4:5], off
	global_load_dword v177, v[2:3], off
	v_lshl_add_u64 v[2:3], v[2:3], 0, s[34:35]
	v_lshl_add_u64 v[4:5], v[4:5], 0, 4
	global_load_dword v178, v[4:5], off
	global_load_dword v179, v[2:3], off
	v_lshl_add_u64 v[2:3], v[2:3], 0, s[34:35]
	v_lshl_add_u64 v[4:5], v[4:5], 0, 4
	global_load_dword v180, v[4:5], off
	global_load_dword v181, v[2:3], off
	v_lshl_add_u64 v[2:3], v[2:3], 0, s[34:35]
	v_lshl_add_u64 v[4:5], v[4:5], 0, 4
	global_load_dword v182, v[4:5], off
	global_load_dword v183, v[2:3], off
	v_lshl_add_u64 v[2:3], v[2:3], 0, s[34:35]
	v_lshl_add_u64 v[4:5], v[4:5], 0, 4
	global_load_dword v184, v[4:5], off
	global_load_dword v185, v[2:3], off
	v_lshl_add_u64 v[2:3], v[2:3], 0, s[34:35]
	v_lshl_add_u64 v[4:5], v[4:5], 0, 4
	global_load_dword v186, v[4:5], off
	global_load_dword v187, v[2:3], off
	v_lshl_add_u64 v[2:3], v[2:3], 0, s[34:35]
	v_lshl_add_u64 v[4:5], v[4:5], 0, 4
	global_load_dword v188, v[4:5], off
	global_load_dword v189, v[2:3], off
	v_lshl_add_u64 v[2:3], v[2:3], 0, s[34:35]
	v_lshl_add_u64 v[4:5], v[4:5], 0, 4
	global_load_dword v190, v[4:5], off
	global_load_dword v191, v[2:3], off
	v_lshl_add_u64 v[2:3], v[2:3], 0, s[34:35]
	v_lshl_add_u64 v[4:5], v[4:5], 0, 4
	s_waitcnt vmcnt(30)
; DI void prep_phase(int ws, PP p, char* shm) {
;     ...
;       const int q = it - n_tr - n_mod, kv = q >> 2, n = (q & 3) * 32 + (tid & 31), kg = tid >> 5;
;       const float* w1 = p->cmp_w1 + (long)kv * 2048 * 128;
;       const float* pe = p->cmp_pos + (long)kv * 2048;
;       float a = 0.f;
;       for (int k = kg * 128; k < kg * 128 + 128; ++k) a += pe[k] * w1[(long)k * 128 + n];
	v_fmac_f32_e32 v6, v160, v161
	s_waitcnt vmcnt(28)
	v_fmac_f32_e32 v6, v162, v163
	s_waitcnt vmcnt(26)
	v_fmac_f32_e32 v6, v164, v165
	s_waitcnt vmcnt(24)
	v_fmac_f32_e32 v6, v166, v167
	s_waitcnt vmcnt(22)
	v_fmac_f32_e32 v6, v168, v169
	s_waitcnt vmcnt(20)
	v_fmac_f32_e32 v6, v170, v171
	s_waitcnt vmcnt(18)
	v_fmac_f32_e32 v6, v172, v173
	s_waitcnt vmcnt(16)
	v_fmac_f32_e32 v6, v174, v175
	s_waitcnt vmcnt(14)
	v_fmac_f32_e32 v6, v176, v177
	s_waitcnt vmcnt(12)
	v_fmac_f32_e32 v6, v178, v179
	s_waitcnt vmcnt(10)
	v_fmac_f32_e32 v6, v180, v181
	s_waitcnt vmcnt(8)
	v_fmac_f32_e32 v6, v182, v183
	s_waitcnt vmcnt(6)
	v_fmac_f32_e32 v6, v184, v185
	s_waitcnt vmcnt(4)
	v_fmac_f32_e32 v6, v186, v187
	s_waitcnt vmcnt(2)
	v_fmac_f32_e32 v6, v188, v189
	s_waitcnt vmcnt(0)
	v_fmac_f32_e32 v6, v190, v191
	global_load_dword v160, v[4:5], off
	global_load_dword v161, v[2:3], off
	v_lshl_add_u64 v[2:3], v[2:3], 0, s[34:35]
	v_lshl_add_u64 v[4:5], v[4:5], 0, 4
	global_load_dword v162, v[4:5], off
	global_load_dword v163, v[2:3], off
	v_lshl_add_u64 v[2:3], v[2:3], 0, s[34:35]
	v_lshl_add_u64 v[4:5], v[4:5], 0, 4
	global_load_dword v164, v[4:5], off
	global_load_dword v165, v[2:3], off
	v_lshl_add_u64 v[2:3], v[2:3], 0, s[34:35]
	v_lshl_add_u64 v[4:5], v[4:5], 0, 4
	global_load_dword v166, v[4:5], off
	global_load_dword v167, v[2:3], off
	v_lshl_add_u64 v[2:3], v[2:3], 0, s[34:35]
	v_lshl_add_u64 v[4:5], v[4:5], 0, 4
	global_load_dword v168, v[4:5], off
	global_load_dword v169, v[2:3], off
	v_lshl_add_u64 v[2:3], v[2:3], 0, s[34:35]
	v_lshl_add_u64 v[4:5], v[4:5], 0, 4
	global_load_dword v170, v[4:5], off
	global_load_dword v171, v[2:3], off
	v_lshl_add_u64 v[2:3], v[2:3], 0, s[34:35]
	v_lshl_add_u64 v[4:5], v[4:5], 0, 4
	global_load_dword v172, v[4:5], off
	global_load_dword v173, v[2:3], off
	v_lshl_add_u64 v[2:3], v[2:3], 0, s[34:35]
	v_lshl_add_u64 v[4:5], v[4:5], 0, 4
	global_load_dword v174, v[4:5], off
	global_load_dword v175, v[2:3], off
	v_lshl_add_u64 v[2:3], v[2:3], 0, s[34:35]
	v_lshl_add_u64 v[4:5], v[4:5], 0, 4
	global_load_dword v176, v[4:5], off
	global_load_dword v177, v[2:3], off
	v_lshl_add_u64 v[2:3], v[2:3], 0, s[34:35]
	v_lshl_add_u64 v[4:5], v[4:5], 0, 4
	global_load_dword v178, v[4:5], off
	global_load_dword v179, v[2:3], off
	v_lshl_add_u64 v[2:3], v[2:3], 0, s[34:35]
	v_lshl_add_u64 v[4:5], v[4:5], 0, 4
	global_load_dword v180, v[4:5], off
	global_load_dword v181, v[2:3], off
	v_lshl_add_u64 v[2:3], v[2:3], 0, s[34:35]
	v_lshl_add_u64 v[4:5], v[4:5], 0, 4
	global_load_dword v182, v[4:5], off
	global_load_dword v183, v[2:3], off
	v_lshl_add_u64 v[2:3], v[2:3], 0, s[34:35]
	v_lshl_add_u64 v[4:5], v[4:5], 0, 4
	global_load_dword v184, v[4:5], off
	global_load_dword v185, v[2:3], off
	v_lshl_add_u64 v[2:3], v[2:3], 0, s[34:35]
	v_lshl_add_u64 v[4:5], v[4:5], 0, 4
	global_load_dword v186, v[4:5], off
	global_load_dword v187, v[2:3], off
	v_lshl_add_u64 v[2:3], v[2:3], 0, s[34:35]
	v_lshl_add_u64 v[4:5], v[4:5], 0, 4
	global_load_dword v188, v[4:5], off
	global_load_dword v189, v[2:3], off
	v_lshl_add_u64 v[2:3], v[2:3], 0, s[34:35]
	v_lshl_add_u64 v[4:5], v[4:5], 0, 4
	global_load_dword v190, v[4:5], off
	global_load_dword v191, v[2:3], off
	v_lshl_add_u64 v[2:3], v[2:3], 0, s[34:35]
	v_lshl_add_u64 v[4:5], v[4:5], 0, 4
	s_waitcnt vmcnt(30)
	v_fmac_f32_e32 v6, v160, v161
	s_waitcnt vmcnt(28)
	v_fmac_f32_e32 v6, v162, v163
	s_waitcnt vmcnt(26)
	v_fmac_f32_e32 v6, v164, v165
	s_waitcnt vmcnt(24)
	v_fmac_f32_e32 v6, v166, v167
	s_waitcnt vmcnt(22)
	v_fmac_f32_e32 v6, v168, v169
	s_waitcnt vmcnt(20)
	v_fmac_f32_e32 v6, v170, v171
	s_waitcnt vmcnt(18)
	v_fmac_f32_e32 v6, v172, v173
	s_waitcnt vmcnt(16)
	v_fmac_f32_e32 v6, v174, v175
	s_waitcnt vmcnt(14)
	v_fmac_f32_e32 v6, v176, v177
	s_waitcnt vmcnt(12)
	v_fmac_f32_e32 v6, v178, v179
	s_waitcnt vmcnt(10)
	v_fmac_f32_e32 v6, v180, v181
	s_waitcnt vmcnt(8)
	v_fmac_f32_e32 v6, v182, v183
	s_waitcnt vmcnt(6)
	v_fmac_f32_e32 v6, v184, v185
	s_waitcnt vmcnt(4)
	v_fmac_f32_e32 v6, v186, v187
	s_waitcnt vmcnt(2)
	v_fmac_f32_e32 v6, v188, v189
	s_waitcnt vmcnt(0)
	v_fmac_f32_e32 v6, v190, v191
	global_load_dword v160, v[4:5], off
	global_load_dword v161, v[2:3], off
	v_lshl_add_u64 v[2:3], v[2:3], 0, s[34:35]
	v_lshl_add_u64 v[4:5], v[4:5], 0, 4
	global_load_dword v162, v[4:5], off
	global_load_dword v163, v[2:3], off
	v_lshl_add_u64 v[2:3], v[2:3], 0, s[34:35]
	v_lshl_add_u64 v[4:5], v[4:5], 0, 4
	global_load_dword v164, v[4:5], off
	global_load_dword v165, v[2:3], off
	v_lshl_add_u64 v[2:3], v[2:3], 0, s[34:35]
	v_lshl_add_u64 v[4:5], v[4:5], 0, 4
	global_load_dword v166, v[4:5], off
	global_load_dword v167, v[2:3], off
	v_lshl_add_u64 v[2:3], v[2:3], 0, s[34:35]
	v_lshl_add_u64 v[4:5], v[4:5], 0, 4
	global_load_dword v168, v[4:5], off
	global_load_dword v169, v[2:3], off
	v_lshl_add_u64 v[2:3], v[2:3], 0, s[34:35]
	v_lshl_add_u64 v[4:5], v[4:5], 0, 4
	global_load_dword v170, v[4:5], off
	global_load_dword v171, v[2:3], off
	v_lshl_add_u64 v[2:3], v[2:3], 0, s[34:35]
	v_lshl_add_u64 v[4:5], v[4:5], 0, 4
	global_load_dword v172, v[4:5], off
	global_load_dword v173, v[2:3], off
	v_lshl_add_u64 v[2:3], v[2:3], 0, s[34:35]
	v_lshl_add_u64 v[4:5], v[4:5], 0, 4
	global_load_dword v174, v[4:5], off
	global_load_dword v175, v[2:3], off
	v_lshl_add_u64 v[2:3], v[2:3], 0, s[34:35]
	v_lshl_add_u64 v[4:5], v[4:5], 0, 4
	global_load_dword v176, v[4:5], off
	global_load_dword v177, v[2:3], off
	v_lshl_add_u64 v[2:3], v[2:3], 0, s[34:35]
	v_lshl_add_u64 v[4:5], v[4:5], 0, 4
	global_load_dword v178, v[4:5], off
	global_load_dword v179, v[2:3], off
	v_lshl_add_u64 v[2:3], v[2:3], 0, s[34:35]
	v_lshl_add_u64 v[4:5], v[4:5], 0, 4
	global_load_dword v180, v[4:5], off
	global_load_dword v181, v[2:3], off
	v_lshl_add_u64 v[2:3], v[2:3], 0, s[34:35]
	v_lshl_add_u64 v[4:5], v[4:5], 0, 4
	global_load_dword v182, v[4:5], off
	global_load_dword v183, v[2:3], off
	v_lshl_add_u64 v[2:3], v[2:3], 0, s[34:35]
	v_lshl_add_u64 v[4:5], v[4:5], 0, 4
	global_load_dword v184, v[4:5], off
	global_load_dword v185, v[2:3], off
	v_lshl_add_u64 v[2:3], v[2:3], 0, s[34:35]
	v_lshl_add_u64 v[4:5], v[4:5], 0, 4
	global_load_dword v186, v[4:5], off
	global_load_dword v187, v[2:3], off
	v_lshl_add_u64 v[2:3], v[2:3], 0, s[34:35]
	v_lshl_add_u64 v[4:5], v[4:5], 0, 4
	global_load_dword v188, v[4:5], off
	global_load_dword v189, v[2:3], off
	v_lshl_add_u64 v[2:3], v[2:3], 0, s[34:35]
	v_lshl_add_u64 v[4:5], v[4:5], 0, 4
	global_load_dword v190, v[4:5], off
	global_load_dword v191, v[2:3], off
	v_lshl_add_u64 v[2:3], v[2:3], 0, s[34:35]
	v_lshl_add_u64 v[4:5], v[4:5], 0, 4
	s_waitcnt vmcnt(30)
; DI void prep_phase(int ws, PP p, char* shm) {
;     ...
;       const int q = it - n_tr - n_mod, kv = q >> 2, n = (q & 3) * 32 + (tid & 31), kg = tid >> 5;
;       const float* w1 = p->cmp_w1 + (long)kv * 2048 * 128;
;       const float* pe = p->cmp_pos + (long)kv * 2048;
;       float a = 0.f;
;       for (int k = kg * 128; k < kg * 128 + 128; ++k) a += pe[k] * w1[(long)k * 128 + n];
	v_fmac_f32_e32 v6, v160, v161
	s_waitcnt vmcnt(28)
	v_fmac_f32_e32 v6, v162, v163
	s_waitcnt vmcnt(26)
	v_fmac_f32_e32 v6, v164, v165
	s_waitcnt vmcnt(24)
	v_fmac_f32_e32 v6, v166, v167
	s_waitcnt vmcnt(22)
	v_fmac_f32_e32 v6, v168, v169
	s_waitcnt vmcnt(20)
	v_fmac_f32_e32 v6, v170, v171
	s_waitcnt vmcnt(18)
	v_fmac_f32_e32 v6, v172, v173
	s_waitcnt vmcnt(16)
	v_fmac_f32_e32 v6, v174, v175
	s_waitcnt vmcnt(14)
	v_fmac_f32_e32 v6, v176, v177
	s_waitcnt vmcnt(12)
	v_fmac_f32_e32 v6, v178, v179
	s_waitcnt vmcnt(10)
	v_fmac_f32_e32 v6, v180, v181
	s_waitcnt vmcnt(8)
	v_fmac_f32_e32 v6, v182, v183
	s_waitcnt vmcnt(6)
	v_fmac_f32_e32 v6, v184, v185
	s_waitcnt vmcnt(4)
	v_fmac_f32_e32 v6, v186, v187
	s_waitcnt vmcnt(2)
	v_fmac_f32_e32 v6, v188, v189
	s_waitcnt vmcnt(0)
	v_fmac_f32_e32 v6, v190, v191
	global_load_dword v160, v[4:5], off
	global_load_dword v161, v[2:3], off
	v_lshl_add_u64 v[2:3], v[2:3], 0, s[34:35]
	v_lshl_add_u64 v[4:5], v[4:5], 0, 4
	global_load_dword v162, v[4:5], off
	global_load_dword v163, v[2:3], off
	v_lshl_add_u64 v[2:3], v[2:3], 0, s[34:35]
	v_lshl_add_u64 v[4:5], v[4:5], 0, 4
	global_load_dword v164, v[4:5], off
	global_load_dword v165, v[2:3], off
	v_lshl_add_u64 v[2:3], v[2:3], 0, s[34:35]
	v_lshl_add_u64 v[4:5], v[4:5], 0, 4
	global_load_dword v166, v[4:5], off
	global_load_dword v167, v[2:3], off
	v_lshl_add_u64 v[2:3], v[2:3], 0, s[34:35]
	v_lshl_add_u64 v[4:5], v[4:5], 0, 4
	global_load_dword v168, v[4:5], off
	global_load_dword v169, v[2:3], off
	v_lshl_add_u64 v[2:3], v[2:3], 0, s[34:35]
	v_lshl_add_u64 v[4:5], v[4:5], 0, 4
	global_load_dword v170, v[4:5], off
	global_load_dword v171, v[2:3], off
	v_lshl_add_u64 v[2:3], v[2:3], 0, s[34:35]
	v_lshl_add_u64 v[4:5], v[4:5], 0, 4
	global_load_dword v172, v[4:5], off
	global_load_dword v173, v[2:3], off
	v_lshl_add_u64 v[2:3], v[2:3], 0, s[34:35]
	v_lshl_add_u64 v[4:5], v[4:5], 0, 4
	global_load_dword v174, v[4:5], off
	global_load_dword v175, v[2:3], off
	v_lshl_add_u64 v[2:3], v[2:3], 0, s[34:35]
	v_lshl_add_u64 v[4:5], v[4:5], 0, 4
	global_load_dword v176, v[4:5], off
	global_load_dword v177, v[2:3], off
	v_lshl_add_u64 v[2:3], v[2:3], 0, s[34:35]
	v_lshl_add_u64 v[4:5], v[4:5], 0, 4
	global_load_dword v178, v[4:5], off
	global_load_dword v179, v[2:3], off
	v_lshl_add_u64 v[2:3], v[2:3], 0, s[34:35]
	v_lshl_add_u64 v[4:5], v[4:5], 0, 4
	global_load_dword v180, v[4:5], off
	global_load_dword v181, v[2:3], off
	v_lshl_add_u64 v[2:3], v[2:3], 0, s[34:35]
	v_lshl_add_u64 v[4:5], v[4:5], 0, 4
	global_load_dword v182, v[4:5], off
	global_load_dword v183, v[2:3], off
	v_lshl_add_u64 v[2:3], v[2:3], 0, s[34:35]
	v_lshl_add_u64 v[4:5], v[4:5], 0, 4
	global_load_dword v184, v[4:5], off
	global_load_dword v185, v[2:3], off
	v_lshl_add_u64 v[2:3], v[2:3], 0, s[34:35]
	v_lshl_add_u64 v[4:5], v[4:5], 0, 4
	global_load_dword v186, v[4:5], off
	global_load_dword v187, v[2:3], off
	v_lshl_add_u64 v[2:3], v[2:3], 0, s[34:35]
	v_lshl_add_u64 v[4:5], v[4:5], 0, 4
	global_load_dword v188, v[4:5], off
	global_load_dword v189, v[2:3], off
	v_lshl_add_u64 v[2:3], v[2:3], 0, s[34:35]
	v_lshl_add_u64 v[4:5], v[4:5], 0, 4
	global_load_dword v190, v[4:5], off
	global_load_dword v191, v[2:3], off
	v_lshl_add_u64 v[2:3], v[2:3], 0, s[34:35]
	v_lshl_add_u64 v[4:5], v[4:5], 0, 4
	s_waitcnt vmcnt(30)
	v_fmac_f32_e32 v6, v160, v161
	s_waitcnt vmcnt(28)
	v_fmac_f32_e32 v6, v162, v163
	s_waitcnt vmcnt(26)
	v_fmac_f32_e32 v6, v164, v165
	s_waitcnt vmcnt(24)
	v_fmac_f32_e32 v6, v166, v167
	s_waitcnt vmcnt(22)
	v_fmac_f32_e32 v6, v168, v169
	s_waitcnt vmcnt(20)
	v_fmac_f32_e32 v6, v170, v171
	s_waitcnt vmcnt(18)
	v_fmac_f32_e32 v6, v172, v173
	s_waitcnt vmcnt(16)
	v_fmac_f32_e32 v6, v174, v175
	s_waitcnt vmcnt(14)
	v_fmac_f32_e32 v6, v176, v177
	s_waitcnt vmcnt(12)
	v_fmac_f32_e32 v6, v178, v179
	s_waitcnt vmcnt(10)
	v_fmac_f32_e32 v6, v180, v181
	s_waitcnt vmcnt(8)
	v_fmac_f32_e32 v6, v182, v183
	s_waitcnt vmcnt(6)
	v_fmac_f32_e32 v6, v184, v185
	s_waitcnt vmcnt(4)
	v_fmac_f32_e32 v6, v186, v187
	s_waitcnt vmcnt(2)
	v_fmac_f32_e32 v6, v188, v189
	s_waitcnt vmcnt(0)
; DI void prep_phase(int ws, PP p, char* shm) {
;     ...
;       for (int k = kg * 128; k < kg * 128 + 128; ++k) a += pe[k] * w1[(long)k * 128 + n];
;       fs[kg * 32 + (tid & 31)] = a;
;       __syncthreads();
;       if (tid < 32) {
;         float s = 0.f;
;         for (int g = 0; g < 16; ++g) s += fs[g * 32 + tid];
;         p->cvec[kv * 128 + (q & 3) * 32 + tid] = s;
	v_fmac_f32_e32 v6, v190, v191
	global_load_dword v160, v[4:5], off
	global_load_dword v161, v[2:3], off
	v_lshl_add_u64 v[2:3], v[2:3], 0, s[34:35]
	v_lshl_add_u64 v[4:5], v[4:5], 0, 4
	global_load_dword v162, v[4:5], off
	global_load_dword v163, v[2:3], off
	v_lshl_add_u64 v[2:3], v[2:3], 0, s[34:35]
	v_lshl_add_u64 v[4:5], v[4:5], 0, 4
	global_load_dword v164, v[4:5], off
	global_load_dword v165, v[2:3], off
	v_lshl_add_u64 v[2:3], v[2:3], 0, s[34:35]
	v_lshl_add_u64 v[4:5], v[4:5], 0, 4
	global_load_dword v166, v[4:5], off
	global_load_dword v167, v[2:3], off
	v_lshl_add_u64 v[2:3], v[2:3], 0, s[34:35]
	v_lshl_add_u64 v[4:5], v[4:5], 0, 4
	global_load_dword v168, v[4:5], off
	global_load_dword v169, v[2:3], off
	v_lshl_add_u64 v[2:3], v[2:3], 0, s[34:35]
	v_lshl_add_u64 v[4:5], v[4:5], 0, 4
	global_load_dword v170, v[4:5], off
	global_load_dword v171, v[2:3], off
	v_lshl_add_u64 v[2:3], v[2:3], 0, s[34:35]
	v_lshl_add_u64 v[4:5], v[4:5], 0, 4
	global_load_dword v172, v[4:5], off
	global_load_dword v173, v[2:3], off
	v_lshl_add_u64 v[2:3], v[2:3], 0, s[34:35]
	v_lshl_add_u64 v[4:5], v[4:5], 0, 4
	global_load_dword v174, v[4:5], off
	global_load_dword v175, v[2:3], off
	v_lshl_add_u64 v[2:3], v[2:3], 0, s[34:35]
	v_lshl_add_u64 v[4:5], v[4:5], 0, 4
	global_load_dword v176, v[4:5], off
	global_load_dword v177, v[2:3], off
	v_lshl_add_u64 v[2:3], v[2:3], 0, s[34:35]
	v_lshl_add_u64 v[4:5], v[4:5], 0, 4
	global_load_dword v178, v[4:5], off
	global_load_dword v179, v[2:3], off
	v_lshl_add_u64 v[2:3], v[2:3], 0, s[34:35]
	v_lshl_add_u64 v[4:5], v[4:5], 0, 4
	global_load_dword v180, v[4:5], off
	global_load_dword v181, v[2:3], off
	v_lshl_add_u64 v[2:3], v[2:3], 0, s[34:35]
	v_lshl_add_u64 v[4:5], v[4:5], 0, 4
	global_load_dword v182, v[4:5], off
	global_load_dword v183, v[2:3], off
	v_lshl_add_u64 v[2:3], v[2:3], 0, s[34:35]
	v_lshl_add_u64 v[4:5], v[4:5], 0, 4
	global_load_dword v184, v[4:5], off
	global_load_dword v185, v[2:3], off
	v_lshl_add_u64 v[2:3], v[2:3], 0, s[34:35]
	v_lshl_add_u64 v[4:5], v[4:5], 0, 4
	global_load_dword v186, v[4:5], off
	global_load_dword v187, v[2:3], off
	v_lshl_add_u64 v[2:3], v[2:3], 0, s[34:35]
	v_lshl_add_u64 v[4:5], v[4:5], 0, 4
	global_load_dword v188, v[4:5], off
	global_load_dword v189, v[2:3], off
	v_lshl_add_u64 v[2:3], v[2:3], 0, s[34:35]
	v_lshl_add_u64 v[4:5], v[4:5], 0, 4
	global_load_dword v190, v[4:5], off
	global_load_dword v191, v[2:3], off
	v_lshl_add_u64 v[2:3], v[2:3], 0, s[34:35]
	v_lshl_add_u64 v[4:5], v[4:5], 0, 4
	s_waitcnt vmcnt(30)
	v_fmac_f32_e32 v6, v160, v161
	s_waitcnt vmcnt(28)
	v_fmac_f32_e32 v6, v162, v163
	s_waitcnt vmcnt(26)
	v_fmac_f32_e32 v6, v164, v165
	s_waitcnt vmcnt(24)
	v_fmac_f32_e32 v6, v166, v167
	s_waitcnt vmcnt(22)
	v_fmac_f32_e32 v6, v168, v169
	s_waitcnt vmcnt(20)
	v_fmac_f32_e32 v6, v170, v171
	s_waitcnt vmcnt(18)
	v_fmac_f32_e32 v6, v172, v173
	s_waitcnt vmcnt(16)
	v_fmac_f32_e32 v6, v174, v175
	s_waitcnt vmcnt(14)
	v_fmac_f32_e32 v6, v176, v177
	s_waitcnt vmcnt(12)
	v_fmac_f32_e32 v6, v178, v179
	s_waitcnt vmcnt(10)
	v_fmac_f32_e32 v6, v180, v181
	s_waitcnt vmcnt(8)
	v_fmac_f32_e32 v6, v182, v183
	s_waitcnt vmcnt(6)
	v_fmac_f32_e32 v6, v184, v185
	s_waitcnt vmcnt(4)
	v_fmac_f32_e32 v6, v186, v187
	s_waitcnt vmcnt(2)
	v_fmac_f32_e32 v6, v188, v189
	s_waitcnt vmcnt(0)
	v_fmac_f32_e32 v6, v190, v191
	s_or_b64 exec, exec, s[16:17]
	ds_write_b32 v66, v6
	s_waitcnt lgkmcnt(0)
	s_barrier
	s_and_saveexec_b64 s[16:17], s[6:7]
	s_cbranch_execz .LBB0_30
	ds_read2_b32 v[2:3], v66 offset1:32
	ds_read2_b32 v[4:5], v66 offset0:64 offset1:96
	ds_read2_b32 v[6:7], v66 offset0:128 offset1:160
	v_add_u32_e32 v8, 0x400, v66
	s_lshl_b32 s15, s18, 5
	s_load_dwordx2 s[18:19], s[24:25], 0x108
	s_waitcnt lgkmcnt(0)
	v_add_f32_e32 v2, 0, v2
	v_add_f32_e32 v2, v2, v3
	v_add_f32_e32 v2, v2, v4
	v_add_f32_e32 v4, v2, v5
	ds_read2_b32 v[2:3], v66 offset0:192 offset1:224
	v_add_f32_e32 v6, v4, v6
	ds_read2_b32 v[4:5], v8 offset1:32
	v_add_f32_e32 v6, v6, v7
	s_and_b32 s15, s15, 0x60
	s_waitcnt lgkmcnt(1)
	v_add_f32_e32 v2, v6, v2
	v_add_f32_e32 v6, v2, v3
	ds_read2_b32 v[2:3], v8 offset0:64 offset1:96
	s_waitcnt lgkmcnt(1)
	v_add_f32_e32 v4, v6, v4
	ds_read2_b32 v[6:7], v8 offset0:128 offset1:160
	v_add_f32_e32 v9, v4, v5
	ds_read2_b32 v[4:5], v8 offset0:192 offset1:224
	s_waitcnt lgkmcnt(2)
	v_add_f32_e32 v2, v9, v2
	v_add_f32_e32 v2, v2, v3
	s_waitcnt lgkmcnt(1)
	v_add_f32_e32 v2, v2, v6
	v_add_f32_e32 v2, v2, v7
	s_lshl_b32 s14, s14, 7
	s_waitcnt lgkmcnt(0)
	v_add_f32_e32 v2, v2, v4
	s_or_b32 s14, s14, s15
	v_add_f32_e32 v4, v2, v5
	v_add_u32_e32 v2, s14, v34
	v_ashrrev_i32_e32 v3, 31, v2
	v_lshl_add_u64 v[2:3], v[2:3], 2, s[18:19]
	global_store_dword v[2:3], v4, off
